# P1: XCD-wise start stagger (8 groups x 0.75 us)
# speedup vs baseline: 1.0058x; 1.0058x over previous
; DEVINL void phase1(const Params& p) {
;     ...
;   for (int t = blockIdx.x; t < ntiles; t += gridDim.x) {
;     int pm = t & 31, pn = t >> 5;
;     gemm_tile<EPI_COLS, false>(p, A, 2048, nullptr, Bt, 2048, 2048, pm * 256, pn * 256, pm * 256, pn * 256);
;   }
.Lq_p1entry:
	s_andn2_b64 vcc, exec, s[58:59]
	s_waitcnt lgkmcnt(0)
	s_barrier
	s_cbranch_vccnz .LBB0_231
	s_cmp_eq_u32 s98, 1
	s_cbranch_scc1 .Lstag_done
	s_bfe_u32 s6, s2, 0x30000
	s_cmp_eq_u32 s6, 0
	s_cbranch_scc1 .Lstag_done
.Lstag_loop:
	s_sleep 24
	s_sub_u32 s6, s6, 1
	s_cmp_lg_u32 s6, 0
	s_cbranch_scc1 .Lstag_loop
